# attention tile loop: wave priority raised while a tile is computed (QK, softmax, PV) and lowered for the staging waits and stores
# speedup vs baseline: 1.0216x; 1.0063x over previous
; __device__ void attn_item(const Params& p, int s_idx, char* smem) {
;     ...
;     auto gload = [&](int kt, KV& st) {
; #pragma unroll
;         for (int i = 0; i < 2; ++i) {
;             const int c = tid + 256 * i, key = c >> 3, dc = c & 7;
;             const bf16_t* src = projb + (size_t)(kt * 64 + key) * NIN + h * 64 + dc * 8;
;             st.rk[i] = *(const u32x4*)(src + 512);
;             const int keyv = c & 63, dcv = c >> 6;
;     ...
;             for (int kk = 0; kk < 4; ++kk) {
;                 const bf16x8 k0 = *(const bf16x8*)(sK + pr * 72 + kk * 16 + hh * 8);
;                 const bf16x8 k1 = *(const bf16x8*)(sK + (32 + pr) * 72 + kk * 16 + hh * 8);
;                 S0 = __builtin_amdgcn_mfma_f32_32x32x16_bf16(k0, qf[kk], S0, 0, 0, 0);
;                 S1 = __builtin_amdgcn_mfma_f32_32x32x16_bf16(k1, qf[kk], S1, 0, 0, 0);
;             }
;             float sv[32];
; #pragma unroll
;             for (int g = 0; g < 4; ++g) {
;                 const int kbase = (g >> 1) * 32 + (g & 1) * 16 + 8 * hh;
;                 const float4 b0 = *(const float4*)(sKb + kbase), b1 = *(const float4*)(sKb + kbase + 4);
;                 const int o = (g & 1) * 8;
;                 if (g >> 1) {
;                     sv[g * 8 + 0] = S1[o + 0] * sc + b0.x; sv[g * 8 + 1] = S1[o + 1] * sc + b0.y; sv[g * 8 + 2] = S1[o + 2] * sc + b0.z; sv[g * 8 + 3] = S1[o + 3] * sc + b0.w;
;                     sv[g * 8 + 4] = S1[o + 4] * sc + b1.x; sv[g * 8 + 5] = S1[o + 5] * sc + b1.y; sv[g * 8 + 6] = S1[o + 6] * sc + b1.z; sv[g * 8 + 7] = S1[o + 7] * sc + b1.w;
;                 } else {
;                     sv[g * 8 + 0] = S0[o + 0] * sc + b0.x; sv[g * 8 + 1] = S0[o + 1] * sc + b0.y; sv[g * 8 + 2] = S0[o + 2] * sc + b0.z; sv[g * 8 + 3] = S0[o + 3] * sc + b0.w;
;                     sv[g * 8 + 4] = S0[o + 4] * sc + b1.x; sv[g * 8 + 5] = S0[o + 5] * sc + b1.y; sv[g * 8 + 6] = S0[o + 6] * sc + b1.z; sv[g * 8 + 7] = S0[o + 7] * sc + b1.w;
;                 }
;             }
;             if (kt * 64 + 63 > wave_q0) {
; #pragma unroll
;                 for (int g = 0; g < 4; ++g) {
;                     const int kbase = kt * 64 + (g >> 1) * 32 + (g & 1) * 16 + 8 * hh;
; #pragma unroll
;                     for (int e = 0; e < 8; ++e) if (kbase + e > qrow) sv[g * 8 + e] = -INFINITY;
;                 }
;             }
.LBB0_110:
	s_cmp_gt_u32 s16, 1
	s_cselect_b32 s32, 0xfffafc00, 0
	global_load_dwordx4 v[92:95], v127, s[34:35] offset:1024
	global_load_dwordx4 v[84:87], v129, s[34:35] offset:2048
	global_load_dwordx4 v[88:91], v128, s[34:35] offset:1024
	global_load_dwordx4 v[80:83], v131, s[34:35] offset:2048
	v_add_u32_e32 v127, s32, v127
	v_add_u32_e32 v129, s32, v129
	v_add_u32_e32 v128, s32, v128
	v_add_u32_e32 v131, s32, v131
	v_lshl_add_u64 v[32:33], s[20:21], 2, v[104:105]
	global_load_dword v158, v[32:33], off offset:-256
	v_cmp_le_i32_e32 vcc, s16, v149
	s_and_saveexec_b64 s[36:37], vcc
	s_cbranch_execz .LBB0_114
	s_setprio 2
	ds_read_b128 v[32:35], v150 offset:4608
	ds_read_b128 v[36:39], v150
	ds_read_b128 v[116:119], v150 offset:32
	ds_read_b128 v[120:123], v150 offset:4640
	s_add_i32 s17, s20, 63
	v_cmp_gt_i32_e32 vcc, s17, v144
	s_waitcnt lgkmcnt(2)
	v_mfma_f32_32x32x16_bf16 v[48:63], v[36:39], v[64:67], 0
	v_mfma_f32_32x32x16_bf16 v[32:47], v[32:35], v[64:67], 0
	s_waitcnt lgkmcnt(1)
	v_mfma_f32_32x32x16_bf16 v[48:63], v[116:119], v[68:71], v[48:63]
	s_waitcnt lgkmcnt(0)
	v_mfma_f32_32x32x16_bf16 v[32:47], v[120:123], v[68:71], v[32:47]
	ds_read_b128 v[116:119], v150 offset:64
	ds_read_b128 v[120:123], v150 offset:4672
	s_waitcnt lgkmcnt(1)
	v_mfma_f32_32x32x16_bf16 v[48:63], v[116:119], v[72:75], v[48:63]
	s_waitcnt lgkmcnt(0)
	v_mfma_f32_32x32x16_bf16 v[32:47], v[120:123], v[72:75], v[32:47]
	ds_read_b128 v[116:119], v150 offset:96
	ds_read_b128 v[120:123], v150 offset:4704
	s_waitcnt lgkmcnt(1)
	v_mfma_f32_32x32x16_bf16 v[48:63], v[116:119], v[76:79], v[48:63]
	ds_read_b128 v[116:119], v151 offset:18432
	ds_read_b128 v[160:163], v151 offset:18448
	s_waitcnt lgkmcnt(2)
	v_mfma_f32_32x32x16_bf16 v[32:47], v[120:123], v[76:79], v[32:47]
	s_waitcnt lgkmcnt(1)
	s_nop 6
	v_fma_f32 v122, v48, s30, v116
	v_fma_f32 v123, v49, s30, v117
	v_fma_f32 v120, v50, s30, v118
	v_fma_f32 v121, v51, s30, v119
	ds_read_b128 v[48:51], v151 offset:18496
	s_waitcnt lgkmcnt(1)
	v_pk_fma_f32 v[118:119], v[52:53], s[30:31], v[160:161] op_sel_hi:[1,0,1]
	v_pk_fma_f32 v[54:55], v[54:55], s[30:31], v[162:163] op_sel_hi:[1,0,1]
	ds_read_b128 v[160:163], v151 offset:18560
	s_waitcnt lgkmcnt(1)
	v_pk_fma_f32 v[116:117], v[56:57], s[30:31], v[48:49] op_sel_hi:[1,0,1]
	v_pk_fma_f32 v[50:51], v[58:59], s[30:31], v[50:51] op_sel_hi:[1,0,1]
	ds_read_b128 v[56:59], v151 offset:18512
	s_waitcnt lgkmcnt(1)
	v_pk_fma_f32 v[52:53], v[34:35], s[30:31], v[162:163] op_sel_hi:[1,0,1]
	s_waitcnt lgkmcnt(0)
	v_pk_fma_f32 v[124:125], v[60:61], s[30:31], v[56:57] op_sel_hi:[1,0,1]
	v_pk_fma_f32 v[60:61], v[62:63], s[30:31], v[58:59] op_sel_hi:[1,0,1]
	v_pk_fma_f32 v[58:59], v[32:33], s[30:31], v[160:161] op_sel_hi:[1,0,1]
	ds_read_b128 v[32:35], v151 offset:18576
	s_waitcnt lgkmcnt(0)
	v_pk_fma_f32 v[56:57], v[36:37], s[30:31], v[32:33] op_sel_hi:[1,0,1]
	v_pk_fma_f32 v[48:49], v[38:39], s[30:31], v[34:35] op_sel_hi:[1,0,1]
	ds_read_b128 v[32:35], v151 offset:18624
	s_waitcnt lgkmcnt(0)
	v_pk_fma_f32 v[38:39], v[40:41], s[30:31], v[32:33] op_sel_hi:[1,0,1]
	v_pk_fma_f32 v[34:35], v[42:43], s[30:31], v[34:35] op_sel_hi:[1,0,1]
	ds_read_b128 v[40:43], v151 offset:18640
	s_waitcnt lgkmcnt(0)
	v_pk_fma_f32 v[36:37], v[44:45], s[30:31], v[40:41] op_sel_hi:[1,0,1]
	v_pk_fma_f32 v[32:33], v[46:47], s[30:31], v[42:43] op_sel_hi:[1,0,1]
	s_and_saveexec_b64 s[42:43], vcc
	s_cbranch_execz .LBB0_113
	v_add_u32_e32 v40, s20, v141
	v_cmp_ge_i32_e32 vcc, v99, v40
	v_or_b32_e32 v41, 3, v40
	v_or_b32_e32 v42, 2, v40
	v_cndmask_b32_e32 v122, v139, v122, vcc
	v_cmp_lt_i32_e32 vcc, v40, v99
	s_nop 1
	v_cndmask_b32_e32 v123, v139, v123, vcc
	v_cmp_le_i32_e32 vcc, v41, v97
	v_or_b32_e32 v41, 5, v40
	s_nop 0
	v_cndmask_b32_e32 v121, v139, v121, vcc
	v_cmp_le_i32_e32 vcc, v42, v98
	v_or_b32_e32 v42, 4, v40
	s_nop 0
	v_cndmask_b32_e32 v120, v139, v120, vcc
	v_cmp_le_i32_e32 vcc, v41, v97
	v_or_b32_e32 v41, 7, v40
	s_nop 0
	v_cndmask_b32_e32 v119, v139, v119, vcc
	v_cmp_le_i32_e32 vcc, v42, v98
	v_or_b32_e32 v42, 6, v40
	s_nop 0
	v_cndmask_b32_e32 v118, v139, v118, vcc
	v_cmp_le_i32_e32 vcc, v41, v97
	v_or_b32_e32 v41, 17, v40
	s_nop 0
	v_cndmask_b32_e32 v55, v139, v55, vcc
	v_cmp_le_i32_e32 vcc, v42, v98
	v_or_b32_e32 v42, 16, v40
	s_nop 0
	v_cndmask_b32_e32 v54, v139, v54, vcc
	v_cmp_le_i32_e32 vcc, v41, v97
	v_or_b32_e32 v41, 19, v40
	s_nop 0
	v_cndmask_b32_e32 v117, v139, v117, vcc
	v_cmp_le_i32_e32 vcc, v42, v98
	v_or_b32_e32 v42, 18, v40
	s_nop 0
	v_cndmask_b32_e32 v116, v139, v116, vcc
	v_cmp_le_i32_e32 vcc, v41, v97
	v_or_b32_e32 v41, 21, v40
	s_nop 0
	v_cndmask_b32_e32 v51, v139, v51, vcc
	v_cmp_le_i32_e32 vcc, v42, v98
	v_or_b32_e32 v42, 20, v40
	s_nop 0
	v_cndmask_b32_e32 v50, v139, v50, vcc
	v_cmp_le_i32_e32 vcc, v41, v97
	v_or_b32_e32 v41, 23, v40
	s_nop 0
	v_cndmask_b32_e32 v125, v139, v125, vcc
	v_cmp_le_i32_e32 vcc, v42, v98
	v_or_b32_e32 v42, 22, v40
	s_nop 0
	v_cndmask_b32_e32 v124, v139, v124, vcc
	v_cmp_le_i32_e32 vcc, v41, v97
	v_or_b32_e32 v41, 33, v40
	s_nop 0
	v_cndmask_b32_e32 v61, v139, v61, vcc
	v_cmp_le_i32_e32 vcc, v42, v98
	v_or_b32_e32 v42, 32, v40
	s_nop 0
	v_cndmask_b32_e32 v60, v139, v60, vcc
	v_cmp_le_i32_e32 vcc, v41, v97
	v_or_b32_e32 v41, 35, v40
	s_nop 0
	v_cndmask_b32_e32 v59, v139, v59, vcc
	v_cmp_le_i32_e32 vcc, v42, v98
	v_or_b32_e32 v42, 34, v40
	s_nop 0
	v_cndmask_b32_e32 v58, v139, v58, vcc
	v_cmp_le_i32_e32 vcc, v41, v97
	v_or_b32_e32 v41, 37, v40
	s_nop 0
	v_cndmask_b32_e32 v53, v139, v53, vcc
	v_cmp_le_i32_e32 vcc, v42, v98
	v_or_b32_e32 v42, 36, v40
	s_nop 0
	v_cndmask_b32_e32 v52, v139, v52, vcc
	v_cmp_le_i32_e32 vcc, v41, v97
	v_or_b32_e32 v41, 39, v40
	s_nop 0
	v_cndmask_b32_e32 v57, v139, v57, vcc
	v_cmp_le_i32_e32 vcc, v42, v98
	v_or_b32_e32 v42, 38, v40
	s_nop 0
	v_cndmask_b32_e32 v56, v139, v56, vcc
	v_cmp_le_i32_e32 vcc, v41, v97
	v_or_b32_e32 v41, 49, v40
	s_nop 0
	v_cndmask_b32_e32 v49, v139, v49, vcc
	v_cmp_le_i32_e32 vcc, v42, v98
	v_or_b32_e32 v42, 48, v40
	s_nop 0
	v_cndmask_b32_e32 v48, v139, v48, vcc
	v_cmp_le_i32_e32 vcc, v41, v97
	v_or_b32_e32 v41, 51, v40
	s_nop 0
	v_cndmask_b32_e32 v39, v139, v39, vcc
	v_cmp_le_i32_e32 vcc, v42, v98
	v_or_b32_e32 v42, 50, v40
	s_nop 0
	v_cndmask_b32_e32 v38, v139, v38, vcc
	v_cmp_le_i32_e32 vcc, v41, v97
	v_or_b32_e32 v41, 53, v40
	s_nop 0
	v_cndmask_b32_e32 v35, v139, v35, vcc
	v_cmp_le_i32_e32 vcc, v42, v98
	v_or_b32_e32 v42, 52, v40
	s_nop 0
	v_cndmask_b32_e32 v34, v139, v34, vcc
	v_cmp_le_i32_e32 vcc, v41, v97
	v_or_b32_e32 v41, 55, v40
	v_or_b32_e32 v40, 54, v40
	v_cndmask_b32_e32 v37, v139, v37, vcc
	v_cmp_le_i32_e32 vcc, v42, v98
	s_nop 1
	v_cndmask_b32_e32 v36, v139, v36, vcc
	v_cmp_le_i32_e32 vcc, v41, v97
	s_nop 1
	v_cndmask_b32_e32 v33, v139, v33, vcc
	v_cmp_le_i32_e32 vcc, v40, v98
	s_nop 1
	v_cndmask_b32_e32 v32, v139, v32, vcc

; __device__ void attn_item(const Params& p, int s_idx, char* smem) {
;     ...
;     auto sstore = [&](int buf, const KV& st) {
;         bf16_t* sK = (bf16_t*)(smem + buf * ATT_BUF); bf16_t* sVt = sK + 64 * 72; float* sKb = (float*)(smem + buf * ATT_BUF + 18432);
; #pragma unroll
;         for (int i = 0; i < 2; ++i) {
;             const int c = tid + 256 * i, key = c >> 3, dc = c & 7;
;             *(u32x4*)(sK + key * 72 + dc * 8) = st.rk[i];
;             const unsigned w0 = st.rv[i].x, w1 = st.rv[i].y, w2 = st.rv[i].z, w3 = st.rv[i].w;
;             bf16_t* d = sVt + ((c >> 6) * 8) * 72 + (c & 63);
;             d[0 * 72] = (bf16_t)(w0 & 0xffffu); d[1 * 72] = (bf16_t)(w0 >> 16);
;             d[2 * 72] = (bf16_t)(w1 & 0xffffu); d[3 * 72] = (bf16_t)(w1 >> 16);
;             d[4 * 72] = (bf16_t)(w2 & 0xffffu); d[5 * 72] = (bf16_t)(w2 >> 16);
;             d[6 * 72] = (bf16_t)(w3 & 0xffffu); d[7 * 72] = (bf16_t)(w3 >> 16);
;         }
;         if (tid < 64) sKb[tid] = st.rkb;
;     };
.LBB0_114:
	s_or_b64 exec, exec, s[36:37]
	s_setprio 0
	s_waitcnt vmcnt(4)
	ds_write_b128 v106, v[92:95] offset:18688
	s_waitcnt vmcnt(3)
	ds_write_b128 v107, v[84:87] offset:27904
	s_waitcnt vmcnt(2)
	ds_write_b128 v108, v[88:91] offset:18688
	s_waitcnt vmcnt(1)
	ds_write_b128 v109, v[80:83] offset:27904
	s_and_saveexec_b64 s[24:25], s[40:41]
	s_cbranch_execz .LBB0_116
	s_waitcnt vmcnt(0)
	ds_write_b32 v147, v158 offset:37120
; __device__ void attn_item(const Params& p, int s_idx, char* smem) {
;     ...
;             for (int kk = 0; kk < 4; ++kk) {
;                 const bf16x8 k0 = *(const bf16x8*)(sK + pr * 72 + kk * 16 + hh * 8);
;                 const bf16x8 k1 = *(const bf16x8*)(sK + (32 + pr) * 72 + kk * 16 + hh * 8);
;                 S0 = __builtin_amdgcn_mfma_f32_32x32x16_bf16(k0, qf[kk], S0, 0, 0, 0);
;                 S1 = __builtin_amdgcn_mfma_f32_32x32x16_bf16(k1, qf[kk], S1, 0, 0, 0);
;             }
;             float sv[32];
; #pragma unroll
;             for (int g = 0; g < 4; ++g) {
;                 const int kbase = (g >> 1) * 32 + (g & 1) * 16 + 8 * hh;
;                 const float4 b0 = *(const float4*)(sKb + kbase), b1 = *(const float4*)(sKb + kbase + 4);
;                 const int o = (g & 1) * 8;
;                 if (g >> 1) {
;                     sv[g * 8 + 0] = S1[o + 0] * sc + b0.x; sv[g * 8 + 1] = S1[o + 1] * sc + b0.y; sv[g * 8 + 2] = S1[o + 2] * sc + b0.z; sv[g * 8 + 3] = S1[o + 3] * sc + b0.w;
;                     sv[g * 8 + 4] = S1[o + 4] * sc + b1.x; sv[g * 8 + 5] = S1[o + 5] * sc + b1.y; sv[g * 8 + 6] = S1[o + 6] * sc + b1.z; sv[g * 8 + 7] = S1[o + 7] * sc + b1.w;
;                 } else {
;                     sv[g * 8 + 0] = S0[o + 0] * sc + b0.x; sv[g * 8 + 1] = S0[o + 1] * sc + b0.y; sv[g * 8 + 2] = S0[o + 2] * sc + b0.z; sv[g * 8 + 3] = S0[o + 3] * sc + b0.w;
;                     sv[g * 8 + 4] = S0[o + 4] * sc + b1.x; sv[g * 8 + 5] = S0[o + 5] * sc + b1.y; sv[g * 8 + 6] = S0[o + 6] * sc + b1.z; sv[g * 8 + 7] = S0[o + 7] * sc + b1.w;
;                 }
;             }
;             if (kt * 64 + 63 > wave_q0) {
; #pragma unroll
;                 for (int g = 0; g < 4; ++g) {
;                     const int kbase = kt * 64 + (g >> 1) * 32 + (g & 1) * 16 + 8 * hh;
; #pragma unroll
;                     for (int e = 0; e < 8; ++e) if (kbase + e > qrow) sv[g * 8 + e] = -INFINITY;
;                 }
;             }
;     ...
;         __syncthreads();
;         gload(min(kt + 2, nkt - 1), sa);
;         compute(kt + 1, 1);
.LBB0_116:
	s_or_b64 exec, exec, s[24:25]
	s_add_i32 s17, s16, -2
	s_max_i32 s18, s17, 0
	s_lshl_b32 s18, s18, 6
	s_waitcnt lgkmcnt(0)
	s_barrier
	global_load_dwordx4 v[92:95], v127, s[34:35] offset:1024
	global_load_dwordx4 v[84:87], v129, s[34:35] offset:2048
	s_mov_b32 s19, s21
	global_load_dwordx4 v[88:91], v128, s[34:35] offset:1024
	global_load_dwordx4 v[80:83], v131, s[34:35] offset:2048
	v_add_u32_e32 v127, s32, v127
	v_add_u32_e32 v129, s32, v129
	v_add_u32_e32 v128, s32, v128
	v_add_u32_e32 v131, s32, v131
	v_lshl_add_u64 v[32:33], s[18:19], 2, v[104:105]
	global_load_dword v158, v[32:33], off
	v_cmp_lt_i32_e32 vcc, s17, v149
	s_and_saveexec_b64 s[36:37], vcc
	s_cbranch_execz .LBB0_120
	s_setprio 2
	ds_read_b128 v[32:35], v150 offset:23296
	ds_read_b128 v[36:39], v150 offset:18688
	ds_read_b128 v[116:119], v150 offset:18720
	ds_read_b128 v[120:123], v150 offset:23328
	s_add_i32 s18, s20, -1
	v_cmp_gt_i32_e32 vcc, s18, v144
	s_waitcnt lgkmcnt(2)
	v_mfma_f32_32x32x16_bf16 v[48:63], v[36:39], v[64:67], 0
	v_mfma_f32_32x32x16_bf16 v[32:47], v[32:35], v[64:67], 0
	s_waitcnt lgkmcnt(1)
	v_mfma_f32_32x32x16_bf16 v[48:63], v[116:119], v[68:71], v[48:63]
	s_waitcnt lgkmcnt(0)
	v_mfma_f32_32x32x16_bf16 v[32:47], v[120:123], v[68:71], v[32:47]
	ds_read_b128 v[116:119], v150 offset:18752
	ds_read_b128 v[120:123], v150 offset:23360
	s_waitcnt lgkmcnt(1)
	v_mfma_f32_32x32x16_bf16 v[48:63], v[116:119], v[72:75], v[48:63]
	s_waitcnt lgkmcnt(0)
	v_mfma_f32_32x32x16_bf16 v[32:47], v[120:123], v[72:75], v[32:47]
	ds_read_b128 v[116:119], v150 offset:18784
	ds_read_b128 v[120:123], v150 offset:23392
	s_waitcnt lgkmcnt(1)
	v_mfma_f32_32x32x16_bf16 v[48:63], v[116:119], v[76:79], v[48:63]
	ds_read_b128 v[116:119], v151 offset:37120
	ds_read_b128 v[160:163], v151 offset:37136
	s_waitcnt lgkmcnt(2)
	v_mfma_f32_32x32x16_bf16 v[32:47], v[120:123], v[76:79], v[32:47]
	s_waitcnt lgkmcnt(1)
	s_nop 6
	v_fma_f32 v122, v48, s30, v116
	v_fma_f32 v123, v49, s30, v117
	v_fma_f32 v120, v50, s30, v118
	v_fma_f32 v121, v51, s30, v119
	ds_read_b128 v[48:51], v151 offset:37184
	s_waitcnt lgkmcnt(1)
	v_pk_fma_f32 v[118:119], v[52:53], s[30:31], v[160:161] op_sel_hi:[1,0,1]
	v_pk_fma_f32 v[54:55], v[54:55], s[30:31], v[162:163] op_sel_hi:[1,0,1]
	ds_read_b128 v[160:163], v151 offset:37248
	s_waitcnt lgkmcnt(1)
	v_pk_fma_f32 v[116:117], v[56:57], s[30:31], v[48:49] op_sel_hi:[1,0,1]
	v_pk_fma_f32 v[50:51], v[58:59], s[30:31], v[50:51] op_sel_hi:[1,0,1]
	ds_read_b128 v[56:59], v151 offset:37200
	s_waitcnt lgkmcnt(1)
	v_pk_fma_f32 v[52:53], v[34:35], s[30:31], v[162:163] op_sel_hi:[1,0,1]
	s_waitcnt lgkmcnt(0)
	v_pk_fma_f32 v[124:125], v[60:61], s[30:31], v[56:57] op_sel_hi:[1,0,1]
	v_pk_fma_f32 v[60:61], v[62:63], s[30:31], v[58:59] op_sel_hi:[1,0,1]
	v_pk_fma_f32 v[58:59], v[32:33], s[30:31], v[160:161] op_sel_hi:[1,0,1]
	ds_read_b128 v[32:35], v151 offset:37264
	s_waitcnt lgkmcnt(0)
	v_pk_fma_f32 v[56:57], v[36:37], s[30:31], v[32:33] op_sel_hi:[1,0,1]
	v_pk_fma_f32 v[48:49], v[38:39], s[30:31], v[34:35] op_sel_hi:[1,0,1]
	ds_read_b128 v[32:35], v151 offset:37312
	s_waitcnt lgkmcnt(0)
	v_pk_fma_f32 v[38:39], v[40:41], s[30:31], v[32:33] op_sel_hi:[1,0,1]
	v_pk_fma_f32 v[34:35], v[42:43], s[30:31], v[34:35] op_sel_hi:[1,0,1]
	ds_read_b128 v[40:43], v151 offset:37328
	s_waitcnt lgkmcnt(0)
	v_pk_fma_f32 v[36:37], v[44:45], s[30:31], v[40:41] op_sel_hi:[1,0,1]
	v_pk_fma_f32 v[32:33], v[46:47], s[30:31], v[42:43] op_sel_hi:[1,0,1]
	s_and_saveexec_b64 s[42:43], vcc
	s_cbranch_execz .LBB0_119
	s_add_i32 s19, s20, 0xffffffc0
	v_add_u32_e32 v40, s19, v141
	v_cmp_ge_i32_e32 vcc, v99, v40
	v_or_b32_e32 v41, 3, v40
	v_or_b32_e32 v42, 2, v40
	v_cndmask_b32_e32 v122, v139, v122, vcc
	v_cmp_lt_i32_e32 vcc, v40, v99
	s_nop 1
	v_cndmask_b32_e32 v123, v139, v123, vcc
	v_cmp_le_i32_e32 vcc, v41, v97
	v_or_b32_e32 v41, 5, v40
	s_nop 0
	v_cndmask_b32_e32 v121, v139, v121, vcc
	v_cmp_le_i32_e32 vcc, v42, v98
	v_or_b32_e32 v42, 4, v40
	s_nop 0
	v_cndmask_b32_e32 v120, v139, v120, vcc
	v_cmp_le_i32_e32 vcc, v41, v97
	v_or_b32_e32 v41, 7, v40
	s_nop 0
	v_cndmask_b32_e32 v119, v139, v119, vcc
	v_cmp_le_i32_e32 vcc, v42, v98
	v_or_b32_e32 v42, 6, v40
	s_nop 0
	v_cndmask_b32_e32 v118, v139, v118, vcc
	v_cmp_le_i32_e32 vcc, v41, v97
	v_or_b32_e32 v41, 17, v40
	s_nop 0
	v_cndmask_b32_e32 v55, v139, v55, vcc
	v_cmp_le_i32_e32 vcc, v42, v98
	v_or_b32_e32 v42, 16, v40
	s_nop 0
	v_cndmask_b32_e32 v54, v139, v54, vcc
	v_cmp_le_i32_e32 vcc, v41, v97
	v_or_b32_e32 v41, 19, v40
	s_nop 0
	v_cndmask_b32_e32 v117, v139, v117, vcc
	v_cmp_le_i32_e32 vcc, v42, v98
	v_or_b32_e32 v42, 18, v40
	s_nop 0
	v_cndmask_b32_e32 v116, v139, v116, vcc
	v_cmp_le_i32_e32 vcc, v41, v97
	v_or_b32_e32 v41, 21, v40
	s_nop 0
	v_cndmask_b32_e32 v51, v139, v51, vcc
	v_cmp_le_i32_e32 vcc, v42, v98
	v_or_b32_e32 v42, 20, v40
	s_nop 0
	v_cndmask_b32_e32 v50, v139, v50, vcc
	v_cmp_le_i32_e32 vcc, v41, v97
	v_or_b32_e32 v41, 23, v40
	s_nop 0
	v_cndmask_b32_e32 v125, v139, v125, vcc
	v_cmp_le_i32_e32 vcc, v42, v98
	v_or_b32_e32 v42, 22, v40
	s_nop 0
	v_cndmask_b32_e32 v124, v139, v124, vcc
	v_cmp_le_i32_e32 vcc, v41, v97
	v_or_b32_e32 v41, 33, v40
	s_nop 0
	v_cndmask_b32_e32 v61, v139, v61, vcc
	v_cmp_le_i32_e32 vcc, v42, v98
	v_or_b32_e32 v42, 32, v40
	s_nop 0
	v_cndmask_b32_e32 v60, v139, v60, vcc
	v_cmp_le_i32_e32 vcc, v41, v97
	v_or_b32_e32 v41, 35, v40
	s_nop 0
	v_cndmask_b32_e32 v59, v139, v59, vcc
	v_cmp_le_i32_e32 vcc, v42, v98
	v_or_b32_e32 v42, 34, v40
	s_nop 0
	v_cndmask_b32_e32 v58, v139, v58, vcc
	v_cmp_le_i32_e32 vcc, v41, v97
	v_or_b32_e32 v41, 37, v40
	s_nop 0
	v_cndmask_b32_e32 v53, v139, v53, vcc
	v_cmp_le_i32_e32 vcc, v42, v98
	v_or_b32_e32 v42, 36, v40
	s_nop 0
	v_cndmask_b32_e32 v52, v139, v52, vcc
	v_cmp_le_i32_e32 vcc, v41, v97
	v_or_b32_e32 v41, 39, v40
	s_nop 0
	v_cndmask_b32_e32 v57, v139, v57, vcc
	v_cmp_le_i32_e32 vcc, v42, v98
	v_or_b32_e32 v42, 38, v40
	s_nop 0
	v_cndmask_b32_e32 v56, v139, v56, vcc
	v_cmp_le_i32_e32 vcc, v41, v97
	v_or_b32_e32 v41, 49, v40
	s_nop 0
	v_cndmask_b32_e32 v49, v139, v49, vcc
	v_cmp_le_i32_e32 vcc, v42, v98
	v_or_b32_e32 v42, 48, v40
	s_nop 0
	v_cndmask_b32_e32 v48, v139, v48, vcc
	v_cmp_le_i32_e32 vcc, v41, v97
	v_or_b32_e32 v41, 51, v40
	s_nop 0
	v_cndmask_b32_e32 v39, v139, v39, vcc
	v_cmp_le_i32_e32 vcc, v42, v98
	v_or_b32_e32 v42, 50, v40
	s_nop 0
	v_cndmask_b32_e32 v38, v139, v38, vcc
	v_cmp_le_i32_e32 vcc, v41, v97
	v_or_b32_e32 v41, 53, v40
	s_nop 0
	v_cndmask_b32_e32 v35, v139, v35, vcc
	v_cmp_le_i32_e32 vcc, v42, v98
	v_or_b32_e32 v42, 52, v40
	s_nop 0
	v_cndmask_b32_e32 v34, v139, v34, vcc
	v_cmp_le_i32_e32 vcc, v41, v97
	v_or_b32_e32 v41, 55, v40
	v_or_b32_e32 v40, 54, v40
	v_cndmask_b32_e32 v37, v139, v37, vcc
	v_cmp_le_i32_e32 vcc, v42, v98
	s_nop 1
	v_cndmask_b32_e32 v36, v139, v36, vcc
	v_cmp_le_i32_e32 vcc, v41, v97
	s_nop 1
	v_cndmask_b32_e32 v33, v139, v33, vcc
	v_cmp_le_i32_e32 vcc, v40, v98
	s_nop 1
	v_cndmask_b32_e32 v32, v139, v32, vcc

; __device__ void attn_item(const Params& p, int s_idx, char* smem) {
;     ...
;     auto sstore = [&](int buf, const KV& st) {
;         bf16_t* sK = (bf16_t*)(smem + buf * ATT_BUF); bf16_t* sVt = sK + 64 * 72; float* sKb = (float*)(smem + buf * ATT_BUF + 18432);
; #pragma unroll
;         for (int i = 0; i < 2; ++i) {
;             const int c = tid + 256 * i, key = c >> 3, dc = c & 7;
;             *(u32x4*)(sK + key * 72 + dc * 8) = st.rk[i];
;             const unsigned w0 = st.rv[i].x, w1 = st.rv[i].y, w2 = st.rv[i].z, w3 = st.rv[i].w;
;             bf16_t* d = sVt + ((c >> 6) * 8) * 72 + (c & 63);
;             d[0 * 72] = (bf16_t)(w0 & 0xffffu); d[1 * 72] = (bf16_t)(w0 >> 16);
;             d[2 * 72] = (bf16_t)(w1 & 0xffffu); d[3 * 72] = (bf16_t)(w1 >> 16);
;             d[4 * 72] = (bf16_t)(w2 & 0xffffu); d[5 * 72] = (bf16_t)(w2 >> 16);
;             d[6 * 72] = (bf16_t)(w3 & 0xffffu); d[7 * 72] = (bf16_t)(w3 >> 16);
;         }
;         if (tid < 64) sKb[tid] = st.rkb;
;     };
;     ...
;         if (kt + 2 < nkt) sstore(0, sa);
.LBB0_120:
	s_or_b64 exec, exec, s[36:37]
	s_setprio 0
	s_cmp_le_u32 s16, 1
	s_cselect_b64 s[36:37], -1, 0
	s_and_b64 vcc, exec, s[36:37]
	s_cbranch_vccnz .LBB0_124
	s_waitcnt vmcnt(4)
	ds_write_b128 v106, v[92:95]
	s_waitcnt vmcnt(3)
	ds_write_b128 v107, v[84:87] offset:9216
	s_waitcnt vmcnt(2)
	ds_write_b128 v108, v[88:91]
	s_waitcnt vmcnt(1)
	ds_write_b128 v109, v[80:83] offset:9216
	s_and_saveexec_b64 s[24:25], s[40:41]
	s_cbranch_execz .LBB0_123
	s_waitcnt vmcnt(0)
	ds_write_b32 v147, v158 offset:18432
